# ev_in epilogue fast path (segments 0-8, tile-uniform): natural bf16 stores staged via wave-private LDS strip into dwordx4 row chunks; transposed stores direct dwordx2; gates segment falls back to comp
# speedup vs baseline: 1.0208x; 1.0079x over previous
.LBB0_268:
	s_lshr_b32 s24, s14, 9
	s_cmp_eq_u32 s24, 9
	s_cbranch_scc1 .Levin1_old
	v_lshl_or_b32 v116, v183, 3, v191
	v_lshrrev_b32_e32 v117, 6, v116
	v_and_b32_e32 v118, 63, v116
	v_lshlrev_b32_e32 v113, 11, v117
	v_add_u32_e32 v113, 0x10000, v113
	v_readfirstlane_b32 s0, v117
	v_and_b32_e32 v116, 31, v118
	v_lshl_add_u32 v112, v116, 1, v113
	v_lshrrev_b32_e32 v117, 5, v118
	v_lshl_add_u32 v112, v117, 8, v112
	v_lshl_add_u32 v113, v118, 4, v113
	v_mul_u32_u24_e32 v115, 0x6000, v116
	v_lshl_add_u32 v115, v117, 3, v115
	v_lshrrev_b32_e32 v117, 2, v118
	v_mul_u32_u24_e32 v117, 0x1c00, v117
	v_and_b32_e32 v114, 3, v118
	v_lshl_add_u32 v114, v114, 4, v117
	s_lshr_b32 s1, s0, 1
	s_lshl_b32 s1, s1, 6
	s_add_u32 s1, s1, s13
	s_and_b32 s0, s0, 1
	s_lshl_b32 s0, s0, 6
	s_and_b32 s2, s14, 0x1ff
	s_add_u32 s0, s0, s2
	s_cmp_lg_u32 s24, 0
	s_cbranch_scc1 .Levin1_noscale
	v_mul_f32_e32 v48, 0x3db504f3, v48
	v_mul_f32_e32 v49, 0x3db504f3, v49
	v_mul_f32_e32 v50, 0x3db504f3, v50
	v_mul_f32_e32 v51, 0x3db504f3, v51
	v_mul_f32_e32 v52, 0x3db504f3, v52
	v_mul_f32_e32 v53, 0x3db504f3, v53
	v_mul_f32_e32 v54, 0x3db504f3, v54
	v_mul_f32_e32 v55, 0x3db504f3, v55
	v_mul_f32_e32 v56, 0x3db504f3, v56
	v_mul_f32_e32 v57, 0x3db504f3, v57
	v_mul_f32_e32 v58, 0x3db504f3, v58
	v_mul_f32_e32 v59, 0x3db504f3, v59
	v_mul_f32_e32 v60, 0x3db504f3, v60
	v_mul_f32_e32 v61, 0x3db504f3, v61
	v_mul_f32_e32 v62, 0x3db504f3, v62
	v_mul_f32_e32 v63, 0x3db504f3, v63
	v_mul_f32_e32 v16, 0x3db504f3, v16
	v_mul_f32_e32 v17, 0x3db504f3, v17
	v_mul_f32_e32 v18, 0x3db504f3, v18
	v_mul_f32_e32 v19, 0x3db504f3, v19
	v_mul_f32_e32 v20, 0x3db504f3, v20
	v_mul_f32_e32 v21, 0x3db504f3, v21
	v_mul_f32_e32 v22, 0x3db504f3, v22
	v_mul_f32_e32 v23, 0x3db504f3, v23
	v_mul_f32_e32 v24, 0x3db504f3, v24
	v_mul_f32_e32 v25, 0x3db504f3, v25
	v_mul_f32_e32 v26, 0x3db504f3, v26
	v_mul_f32_e32 v27, 0x3db504f3, v27
	v_mul_f32_e32 v28, 0x3db504f3, v28
	v_mul_f32_e32 v29, 0x3db504f3, v29
	v_mul_f32_e32 v30, 0x3db504f3, v30
	v_mul_f32_e32 v31, 0x3db504f3, v31
	v_mul_f32_e32 v32, 0x3db504f3, v32
	v_mul_f32_e32 v33, 0x3db504f3, v33
	v_mul_f32_e32 v34, 0x3db504f3, v34
	v_mul_f32_e32 v35, 0x3db504f3, v35
	v_mul_f32_e32 v36, 0x3db504f3, v36
	v_mul_f32_e32 v37, 0x3db504f3, v37
	v_mul_f32_e32 v38, 0x3db504f3, v38
	v_mul_f32_e32 v39, 0x3db504f3, v39
	v_mul_f32_e32 v40, 0x3db504f3, v40
	v_mul_f32_e32 v41, 0x3db504f3, v41
	v_mul_f32_e32 v42, 0x3db504f3, v42
	v_mul_f32_e32 v43, 0x3db504f3, v43
	v_mul_f32_e32 v44, 0x3db504f3, v44
	v_mul_f32_e32 v45, 0x3db504f3, v45
	v_mul_f32_e32 v46, 0x3db504f3, v46
	v_mul_f32_e32 v47, 0x3db504f3, v47
	v_mul_f32_e32 v0, 0x3db504f3, v0
	v_mul_f32_e32 v1, 0x3db504f3, v1
	v_mul_f32_e32 v2, 0x3db504f3, v2
	v_mul_f32_e32 v3, 0x3db504f3, v3
	v_mul_f32_e32 v4, 0x3db504f3, v4
	v_mul_f32_e32 v5, 0x3db504f3, v5
	v_mul_f32_e32 v6, 0x3db504f3, v6
	v_mul_f32_e32 v7, 0x3db504f3, v7
	v_mul_f32_e32 v8, 0x3db504f3, v8
	v_mul_f32_e32 v9, 0x3db504f3, v9
	v_mul_f32_e32 v10, 0x3db504f3, v10
	v_mul_f32_e32 v11, 0x3db504f3, v11
	v_mul_f32_e32 v12, 0x3db504f3, v12
	v_mul_f32_e32 v13, 0x3db504f3, v13
	v_mul_f32_e32 v14, 0x3db504f3, v14
	v_mul_f32_e32 v15, 0x3db504f3, v15
.Levin1_noscale:
	s_mov_b32 s2, -1
	s_cmp_eq_u32 s24, 1
	s_cselect_b32 s2, 0, s2
	s_cmp_eq_u32 s24, 2
	s_cselect_b32 s2, 0x200, s2
	s_cmp_eq_u32 s24, 7
	s_cselect_b32 s2, 0x400, s2
	s_cmp_lt_i32 s2, 0
	s_cbranch_scc1 .Levin1_notr
	s_add_u32 s2, s2, s0
	s_mul_i32 s2, s2, 0x6000
	s_lshl_b32 s3, s1, 1
	s_add_u32 s2, s2, s3
	s_add_u32 s98, s90, 0x8d71900
	s_addc_u32 s99, s91, 0
	s_add_u32 s98, s98, s2
	s_addc_u32 s99, s99, 0
	s_add_u32 s100, s98, 0xc0000
	s_addc_u32 s101, s99, 0
	v_cvt_pk_bf16_f32 v64, v48, v49
	v_cvt_pk_bf16_f32 v65, v50, v51
	global_store_dwordx2 v115, v[64:65], s[98:99]
	v_cvt_pk_bf16_f32 v66, v52, v53
	v_cvt_pk_bf16_f32 v67, v54, v55
	global_store_dwordx2 v115, v[66:67], s[98:99] offset:16
	v_cvt_pk_bf16_f32 v68, v56, v57
	v_cvt_pk_bf16_f32 v69, v58, v59
	global_store_dwordx2 v115, v[68:69], s[98:99] offset:32
	v_cvt_pk_bf16_f32 v70, v60, v61
	v_cvt_pk_bf16_f32 v71, v62, v63
	global_store_dwordx2 v115, v[70:71], s[98:99] offset:48
	v_cvt_pk_bf16_f32 v72, v32, v33
	v_cvt_pk_bf16_f32 v73, v34, v35
	global_store_dwordx2 v115, v[72:73], s[98:99] offset:64
	v_cvt_pk_bf16_f32 v74, v36, v37
	v_cvt_pk_bf16_f32 v75, v38, v39
	global_store_dwordx2 v115, v[74:75], s[98:99] offset:80
	v_cvt_pk_bf16_f32 v76, v40, v41
	v_cvt_pk_bf16_f32 v77, v42, v43
	global_store_dwordx2 v115, v[76:77], s[98:99] offset:96
	v_cvt_pk_bf16_f32 v78, v44, v45
	v_cvt_pk_bf16_f32 v79, v46, v47
	global_store_dwordx2 v115, v[78:79], s[98:99] offset:112
	v_cvt_pk_bf16_f32 v80, v16, v17
	v_cvt_pk_bf16_f32 v81, v18, v19
	global_store_dwordx2 v115, v[80:81], s[100:101]
	v_cvt_pk_bf16_f32 v82, v20, v21
	v_cvt_pk_bf16_f32 v83, v22, v23
	global_store_dwordx2 v115, v[82:83], s[100:101] offset:16
	v_cvt_pk_bf16_f32 v84, v24, v25
	v_cvt_pk_bf16_f32 v85, v26, v27
	global_store_dwordx2 v115, v[84:85], s[100:101] offset:32
	v_cvt_pk_bf16_f32 v86, v28, v29
	v_cvt_pk_bf16_f32 v87, v30, v31
	global_store_dwordx2 v115, v[86:87], s[100:101] offset:48
	v_cvt_pk_bf16_f32 v88, v0, v1
	v_cvt_pk_bf16_f32 v89, v2, v3
	global_store_dwordx2 v115, v[88:89], s[100:101] offset:64
	v_cvt_pk_bf16_f32 v90, v4, v5
	v_cvt_pk_bf16_f32 v91, v6, v7
	global_store_dwordx2 v115, v[90:91], s[100:101] offset:80
	v_cvt_pk_bf16_f32 v92, v8, v9
	v_cvt_pk_bf16_f32 v93, v10, v11
	global_store_dwordx2 v115, v[92:93], s[100:101] offset:96
	v_cvt_pk_bf16_f32 v94, v12, v13
	v_cvt_pk_bf16_f32 v95, v14, v15
	global_store_dwordx2 v115, v[94:95], s[100:101] offset:112
.Levin1_notr:
	s_cmp_eq_u32 s24, 2
	s_cbranch_scc1 .LBB0_259
	s_cmp_eq_u32 s24, 7
	s_cbranch_scc1 .LBB0_259
	s_cmp_ge_u32 s24, 3
	s_cselect_b32 s2, 1, 0
	s_sub_u32 s2, s24, s2
	s_cmp_ge_u32 s24, 8
	s_cselect_b32 s3, 1, 0
	s_sub_u32 s2, s2, s3
	s_lshl_b32 s2, s2, 9
	s_add_u32 s2, s2, s0
	s_lshl_b32 s2, s2, 1
	s_mul_i32 s3, s1, 0x1c00
	s_add_u32 s2, s2, s3
	s_add_u32 s98, s90, 0x3971900
	s_addc_u32 s99, s91, 0
	s_add_u32 s98, s98, s2
	s_addc_u32 s99, s99, 0
	v_cvt_pk_bf16_f32 v64, v48, v49
	v_cvt_pk_bf16_f32 v65, v50, v51
	v_cvt_pk_bf16_f32 v66, v52, v53
	v_cvt_pk_bf16_f32 v67, v54, v55
	v_cvt_pk_bf16_f32 v68, v56, v57
	v_cvt_pk_bf16_f32 v69, v58, v59
	v_cvt_pk_bf16_f32 v70, v60, v61
	v_cvt_pk_bf16_f32 v71, v62, v63
	ds_write_b16 v112, v64
	ds_write_b16_d16_hi v112, v64 offset:64
	ds_write_b16 v112, v65 offset:128
	ds_write_b16_d16_hi v112, v65 offset:192
	ds_write_b16 v112, v66 offset:512
	ds_write_b16_d16_hi v112, v66 offset:576
	ds_write_b16 v112, v67 offset:640
	ds_write_b16_d16_hi v112, v67 offset:704
	ds_write_b16 v112, v68 offset:1024
	ds_write_b16_d16_hi v112, v68 offset:1088
	ds_write_b16 v112, v69 offset:1152
	ds_write_b16_d16_hi v112, v69 offset:1216
	ds_write_b16 v112, v70 offset:1536
	ds_write_b16_d16_hi v112, v70 offset:1600
	ds_write_b16 v112, v71 offset:1664
	ds_write_b16_d16_hi v112, v71 offset:1728
	ds_read_b128 v[120:123], v113
	ds_read_b128 v[124:127], v113 offset:1024
	s_waitcnt lgkmcnt(0)
	global_store_dwordx4 v114, v[120:123], s[98:99]
	s_add_u32 s100, s98, 0x1c000
	s_addc_u32 s101, s99, 0
	global_store_dwordx4 v114, v[124:127], s[100:101]
	v_cvt_pk_bf16_f32 v72, v16, v17
	v_cvt_pk_bf16_f32 v73, v18, v19
	v_cvt_pk_bf16_f32 v74, v20, v21
	v_cvt_pk_bf16_f32 v75, v22, v23
	v_cvt_pk_bf16_f32 v76, v24, v25
	v_cvt_pk_bf16_f32 v77, v26, v27
	v_cvt_pk_bf16_f32 v78, v28, v29
	v_cvt_pk_bf16_f32 v79, v30, v31
	ds_write_b16 v112, v72
	ds_write_b16_d16_hi v112, v72 offset:64
	ds_write_b16 v112, v73 offset:128
	ds_write_b16_d16_hi v112, v73 offset:192
	ds_write_b16 v112, v74 offset:512
	ds_write_b16_d16_hi v112, v74 offset:576
	ds_write_b16 v112, v75 offset:640
	ds_write_b16_d16_hi v112, v75 offset:704
	ds_write_b16 v112, v76 offset:1024
	ds_write_b16_d16_hi v112, v76 offset:1088
	ds_write_b16 v112, v77 offset:1152
	ds_write_b16_d16_hi v112, v77 offset:1216
	ds_write_b16 v112, v78 offset:1536
	ds_write_b16_d16_hi v112, v78 offset:1600
	ds_write_b16 v112, v79 offset:1664
	ds_write_b16_d16_hi v112, v79 offset:1728
	ds_read_b128 v[120:123], v113
	ds_read_b128 v[124:127], v113 offset:1024
	s_waitcnt lgkmcnt(0)
	global_store_dwordx4 v114, v[120:123], s[98:99] offset:64
	global_store_dwordx4 v114, v[124:127], s[100:101] offset:64
	s_add_u32 s98, s98, 0x38000
	s_addc_u32 s99, s99, 0
	v_cvt_pk_bf16_f32 v64, v32, v33
	v_cvt_pk_bf16_f32 v65, v34, v35
	v_cvt_pk_bf16_f32 v66, v36, v37
	v_cvt_pk_bf16_f32 v67, v38, v39
	v_cvt_pk_bf16_f32 v68, v40, v41
	v_cvt_pk_bf16_f32 v69, v42, v43
	v_cvt_pk_bf16_f32 v70, v44, v45
	v_cvt_pk_bf16_f32 v71, v46, v47
	ds_write_b16 v112, v64
	ds_write_b16_d16_hi v112, v64 offset:64
	ds_write_b16 v112, v65 offset:128
	ds_write_b16_d16_hi v112, v65 offset:192
	ds_write_b16 v112, v66 offset:512
	ds_write_b16_d16_hi v112, v66 offset:576
	ds_write_b16 v112, v67 offset:640
	ds_write_b16_d16_hi v112, v67 offset:704
	ds_write_b16 v112, v68 offset:1024
	ds_write_b16_d16_hi v112, v68 offset:1088
	ds_write_b16 v112, v69 offset:1152
	ds_write_b16_d16_hi v112, v69 offset:1216
	ds_write_b16 v112, v70 offset:1536
	ds_write_b16_d16_hi v112, v70 offset:1600
	ds_write_b16 v112, v71 offset:1664
	ds_write_b16_d16_hi v112, v71 offset:1728
	ds_read_b128 v[120:123], v113
	ds_read_b128 v[124:127], v113 offset:1024
	s_waitcnt lgkmcnt(0)
	global_store_dwordx4 v114, v[120:123], s[98:99]
	s_add_u32 s100, s98, 0x1c000
	s_addc_u32 s101, s99, 0
	global_store_dwordx4 v114, v[124:127], s[100:101]
	v_cvt_pk_bf16_f32 v72, v0, v1
	v_cvt_pk_bf16_f32 v73, v2, v3
	v_cvt_pk_bf16_f32 v74, v4, v5
	v_cvt_pk_bf16_f32 v75, v6, v7
	v_cvt_pk_bf16_f32 v76, v8, v9
	v_cvt_pk_bf16_f32 v77, v10, v11
	v_cvt_pk_bf16_f32 v78, v12, v13
	v_cvt_pk_bf16_f32 v79, v14, v15
	ds_write_b16 v112, v72
	ds_write_b16_d16_hi v112, v72 offset:64
	ds_write_b16 v112, v73 offset:128
	ds_write_b16_d16_hi v112, v73 offset:192
	ds_write_b16 v112, v74 offset:512
	ds_write_b16_d16_hi v112, v74 offset:576
	ds_write_b16 v112, v75 offset:640
	ds_write_b16_d16_hi v112, v75 offset:704
	ds_write_b16 v112, v76 offset:1024
	ds_write_b16_d16_hi v112, v76 offset:1088
	ds_write_b16 v112, v77 offset:1152
	ds_write_b16_d16_hi v112, v77 offset:1216
	ds_write_b16 v112, v78 offset:1536
	ds_write_b16_d16_hi v112, v78 offset:1600
	ds_write_b16 v112, v79 offset:1664
	ds_write_b16_d16_hi v112, v79 offset:1728
	ds_read_b128 v[120:123], v113
	ds_read_b128 v[124:127], v113 offset:1024
	s_waitcnt lgkmcnt(0)
	global_store_dwordx4 v114, v[120:123], s[98:99] offset:64
	global_store_dwordx4 v114, v[124:127], s[100:101] offset:64
	s_branch .LBB0_259
